# EpiIn row statistics rewrite also in the P2h in-projection tail GEMM instance
# baseline (speedup 1.0000x reference)
; __device__ __forceinline__ void load_rstd8(const float* ssq, const float* ssqc, int row0, int fq, float (&rs)[2][4]) {
;     const bool isc = row0 >= ML;
; #pragma unroll
;     for (int ai = 0; ai < 2; ++ai)
; #pragma unroll
;         for (int m = 0; m < 4; ++m) {
;             const int row = row0 + ai * HALF + m * 16;
;             float s;
;             if (!isc) { const f32x4 a = *(const f32x4*)(ssq + ((size_t)(2 * fq) * MT + row) * 4), b = *(const f32x4*)(ssq + ((size_t)(2 * fq + 1) * MT + row) * 4);
;                 s = ((a[0] + a[1]) + (a[2] + a[3])) + ((b[0] + b[1]) + (b[2] + b[3])); }
.LBB0_405:
	s_lshl_b32 s40, s94, 8
	s_add_u32 s40, s40, s71
	v_add_u32_e32 v240, s40, v189
	v_xor_b32_e32 v243, 16, v201
	v_lshlrev_b32_e32 v243, 2, v243
	v_xor_b32_e32 v244, 32, v201
	v_lshlrev_b32_e32 v244, 2, v244
	s_cmp_ge_u32 s94, 32
	s_cbranch_scc1 .Lepiin_ctx_p2h
	v_mul_u32_u24_e32 v228, 0x4400, v191
	v_add_u32_e32 v228, v228, v240
	v_lshlrev_b32_e32 v241, 4, v228
	v_add_u32_e32 v242, 0x22000, v241
	global_load_dwordx4 v[130:133], v241, s[46:47]
	global_load_dwordx4 v[134:137], v242, s[46:47]
	global_load_dwordx4 v[138:141], v241, s[46:47] offset:256
	global_load_dwordx4 v[142:145], v242, s[46:47] offset:256
	global_load_dwordx4 v[146:149], v241, s[46:47] offset:512
	global_load_dwordx4 v[150:153], v242, s[46:47] offset:512
	global_load_dwordx4 v[168:171], v241, s[46:47] offset:768
	global_load_dwordx4 v[172:175], v242, s[46:47] offset:768
	global_load_dwordx4 v[176:179], v241, s[46:47] offset:2048
	global_load_dwordx4 v[180:183], v242, s[46:47] offset:2048
	global_load_dwordx4 v[184:187], v241, s[46:47] offset:2304
	global_load_dwordx4 v[204:207], v242, s[46:47] offset:2304
	global_load_dwordx4 v[208:211], v241, s[46:47] offset:2560
	global_load_dwordx4 v[212:215], v242, s[46:47] offset:2560
	global_load_dwordx4 v[216:219], v241, s[46:47] offset:2816
	global_load_dwordx4 v[220:223], v242, s[46:47] offset:2816
	s_waitcnt vmcnt(15)
	v_add_f32_e32 v130, v130, v131
	v_add_f32_e32 v132, v132, v133
	s_waitcnt vmcnt(14)
	v_add_f32_e32 v134, v134, v135
	v_add_f32_e32 v136, v136, v137
	v_add_f32_e32 v130, v130, v132
	v_add_f32_e32 v134, v134, v136
	v_add_f32_e32 v130, v130, v134
	s_waitcnt vmcnt(13)
	v_add_f32_e32 v138, v138, v139
	v_add_f32_e32 v140, v140, v141
	s_waitcnt vmcnt(12)
	v_add_f32_e32 v142, v142, v143
	v_add_f32_e32 v144, v144, v145
	v_add_f32_e32 v138, v138, v140
	v_add_f32_e32 v142, v142, v144
	v_add_f32_e32 v138, v138, v142
	s_waitcnt vmcnt(11)
	v_add_f32_e32 v146, v146, v147
	v_add_f32_e32 v148, v148, v149
	s_waitcnt vmcnt(10)
	v_add_f32_e32 v150, v150, v151
	v_add_f32_e32 v152, v152, v153
	v_add_f32_e32 v146, v146, v148
	v_add_f32_e32 v150, v150, v152
	v_add_f32_e32 v146, v146, v150
	s_waitcnt vmcnt(9)
	v_add_f32_e32 v168, v168, v169
	v_add_f32_e32 v170, v170, v171
	s_waitcnt vmcnt(8)
	v_add_f32_e32 v172, v172, v173
	v_add_f32_e32 v174, v174, v175
	v_add_f32_e32 v168, v168, v170
	v_add_f32_e32 v172, v172, v174
	v_add_f32_e32 v168, v168, v172
	s_waitcnt vmcnt(7)
	v_add_f32_e32 v176, v176, v177
	v_add_f32_e32 v178, v178, v179
	s_waitcnt vmcnt(6)
	v_add_f32_e32 v180, v180, v181
	v_add_f32_e32 v182, v182, v183
	v_add_f32_e32 v176, v176, v178
	v_add_f32_e32 v180, v180, v182
	v_add_f32_e32 v176, v176, v180
	s_waitcnt vmcnt(5)
	v_add_f32_e32 v184, v184, v185
	v_add_f32_e32 v186, v186, v187
	s_waitcnt vmcnt(4)
	v_add_f32_e32 v204, v204, v205
	v_add_f32_e32 v206, v206, v207
	v_add_f32_e32 v184, v184, v186
	v_add_f32_e32 v204, v204, v206
	v_add_f32_e32 v184, v184, v204
	s_waitcnt vmcnt(3)
	v_add_f32_e32 v208, v208, v209
	v_add_f32_e32 v210, v210, v211
	s_waitcnt vmcnt(2)
	v_add_f32_e32 v212, v212, v213
	v_add_f32_e32 v214, v214, v215
	v_add_f32_e32 v208, v208, v210
	v_add_f32_e32 v212, v212, v214
	v_add_f32_e32 v208, v208, v212
	s_waitcnt vmcnt(1)
	v_add_f32_e32 v216, v216, v217
	v_add_f32_e32 v218, v218, v219
	s_waitcnt vmcnt(0)
	v_add_f32_e32 v220, v220, v221
	v_add_f32_e32 v222, v222, v223
	v_add_f32_e32 v216, v216, v218
	v_add_f32_e32 v220, v220, v222
	v_add_f32_e32 v216, v216, v220
	s_branch .Lepiin_join_p2h

; __device__ __forceinline__ void load_rstd8(const float* ssq, const float* ssqc, int row0, int fq, float (&rs)[2][4]) {
;     ...
;             s += __shfl_xor(s, 16); s += __shfl_xor(s, 32);
;             rs[ai][m] = 1.0f / sqrtf(s * (1.0f / D) + EPS);
;     __device__ __forceinline__ void operator()(const f32x4 (&acc)[2][2][4][2], const Unit& u, int wr, int wc, int fr_, int fq_) const {
;     ...
;         const int cpos = wc * 32 + 8 * fq;
;         const int colb = pn * BM + cpos;
;         f32x4 sh[2][2];
; #pragma unroll
;         for (int bj = 0; bj < 2; ++bj)
; #pragma unroll
;             for (int n = 0; n < 2; ++n) { const int dsrc = (wc < 2 ? 16 * wc + 4 * fq : 16 * wc + 4 * fq + 32) + 32 * n;
;                 sh[bj][n] = *(const f32x4*)(shw + (size_t)v * INW + (pn >= 12 && pn < 17 ? pn * BM + bj * HALF + dsrc : colb + bj * HALF + 4 * n)); }
.Lepiin_join_p2h:
	s_waitcnt vmcnt(0)
	ds_bpermute_b32 v228, v243, v130
	ds_bpermute_b32 v229, v243, v138
	ds_bpermute_b32 v230, v243, v146
	ds_bpermute_b32 v231, v243, v168
	ds_bpermute_b32 v232, v243, v176
	ds_bpermute_b32 v233, v243, v184
	ds_bpermute_b32 v234, v243, v208
	ds_bpermute_b32 v235, v243, v216
	s_waitcnt lgkmcnt(7)
	v_add_f32_e32 v130, v130, v228
	s_waitcnt lgkmcnt(6)
	v_add_f32_e32 v138, v138, v229
	s_waitcnt lgkmcnt(5)
	v_add_f32_e32 v146, v146, v230
	s_waitcnt lgkmcnt(4)
	v_add_f32_e32 v168, v168, v231
	s_waitcnt lgkmcnt(3)
	v_add_f32_e32 v176, v176, v232
	s_waitcnt lgkmcnt(2)
	v_add_f32_e32 v184, v184, v233
	s_waitcnt lgkmcnt(1)
	v_add_f32_e32 v208, v208, v234
	s_waitcnt lgkmcnt(0)
	v_add_f32_e32 v216, v216, v235
	ds_bpermute_b32 v228, v244, v130
	ds_bpermute_b32 v229, v244, v138
	ds_bpermute_b32 v230, v244, v146
	ds_bpermute_b32 v231, v244, v168
	ds_bpermute_b32 v232, v244, v176
	ds_bpermute_b32 v233, v244, v184
	ds_bpermute_b32 v234, v244, v208
	ds_bpermute_b32 v235, v244, v216
	s_waitcnt lgkmcnt(7)
	v_add_f32_e32 v130, v130, v228
	s_waitcnt lgkmcnt(6)
	v_add_f32_e32 v138, v138, v229
	s_waitcnt lgkmcnt(5)
	v_add_f32_e32 v146, v146, v230
	s_waitcnt lgkmcnt(4)
	v_add_f32_e32 v168, v168, v231
	s_waitcnt lgkmcnt(3)
	v_add_f32_e32 v176, v176, v232
	s_waitcnt lgkmcnt(2)
	v_add_f32_e32 v184, v184, v233
	s_waitcnt lgkmcnt(1)
	v_add_f32_e32 v208, v208, v234
	s_waitcnt lgkmcnt(0)
	v_add_f32_e32 v216, v216, v235
	v_fmamk_f32 v130, v130, 0x3a000000, v195
	v_fmamk_f32 v138, v138, 0x3a000000, v195
	v_fmamk_f32 v146, v146, 0x3a000000, v195
	v_fmamk_f32 v168, v168, 0x3a000000, v195
	v_fmamk_f32 v176, v176, 0x3a000000, v195
	v_fmamk_f32 v184, v184, 0x3a000000, v195
	v_fmamk_f32 v208, v208, 0x3a000000, v195
	v_fmamk_f32 v216, v216, 0x3a000000, v195
	v_rsq_f32_e32 v134, v130
	v_rsq_f32_e32 v142, v138
	v_rsq_f32_e32 v150, v146
	v_rsq_f32_e32 v172, v168
	v_rsq_f32_e32 v180, v176
	v_rsq_f32_e32 v204, v184
	v_rsq_f32_e32 v212, v208
	v_rsq_f32_e32 v220, v216
	v_mul_f32_e32 v228, v130, v134
	v_mul_f32_e32 v229, v138, v142
	v_mul_f32_e32 v230, v146, v150
	v_mul_f32_e32 v231, v168, v172
	v_mul_f32_e32 v232, v176, v180
	v_mul_f32_e32 v233, v184, v204
	v_mul_f32_e32 v234, v208, v212
	v_mul_f32_e32 v235, v216, v220
	v_fma_f32 v228, -v228, v134, 1.0
	v_fma_f32 v229, -v229, v142, 1.0
	v_fma_f32 v230, -v230, v150, 1.0
	v_fma_f32 v231, -v231, v172, 1.0
	v_fma_f32 v232, -v232, v180, 1.0
	v_fma_f32 v233, -v233, v204, 1.0
	v_fma_f32 v234, -v234, v212, 1.0
	v_fma_f32 v235, -v235, v220, 1.0
	v_mul_f32_e32 v130, 0.5, v134
	v_mul_f32_e32 v138, 0.5, v142
	v_mul_f32_e32 v146, 0.5, v150
	v_mul_f32_e32 v168, 0.5, v172
	v_mul_f32_e32 v176, 0.5, v180
	v_mul_f32_e32 v184, 0.5, v204
	v_mul_f32_e32 v208, 0.5, v212
	v_mul_f32_e32 v216, 0.5, v220
	v_fma_f32 v200, v130, v228, v134
	v_fma_f32 v198, v138, v229, v142
	v_fma_f32 v196, v146, v230, v150
	v_fma_f32 v192, v168, v231, v172
	v_fma_f32 v190, v176, v232, v180
	v_fma_f32 v188, v184, v233, v204
	v_fma_f32 v0, v208, v234, v212
	v_fma_f32 v194, v216, v235, v220
	s_waitcnt lgkmcnt(0)
	v_mov_b32_e32 v240, v189
	v_mov_b32_e32 v150, v191
	s_lshl_b32 s26, s94, 8
	s_add_i32 s26, s26, s71
	v_add_u32_e32 v168, s26, v240
	v_ashrrev_i32_e32 v169, 31, v168
	v_lshlrev_b32_e32 v130, 3, v150
	v_add_u32_e32 v174, 16, v168
	v_ashrrev_i32_e32 v175, 31, v174
	v_add_u32_e32 v176, 32, v168
	v_ashrrev_i32_e32 v177, 31, v176
	v_add_u32_e32 v178, 48, v168
	v_ashrrev_i32_e32 v179, 31, v178
	v_add_u32_e32 v180, 0x80, v168
	v_ashrrev_i32_e32 v181, 31, v180
	v_add_u32_e32 v182, 0x90, v168
	v_ashrrev_i32_e32 v183, 31, v182
	v_add_u32_e32 v184, 0xa0, v168
	v_ashrrev_i32_e32 v185, 31, v184
	v_lshlrev_b64 v[206:207], 11, v[134:135]
	v_lshl_add_u64 v[206:207], v[186:187], 0, v[206:207]
	v_add_u32_e32 v186, 0xb0, v168
	v_ashrrev_i32_e32 v187, 31, v186
	s_add_i32 s42, s95, 15
	s_lshl_b32 s26, s42, 8
	s_cmp_lt_u32 s94, 32
	v_add_u32_e32 v202, s90, v130
	v_lshlrev_b32_e32 v130, 2, v150
	v_add_u32_e32 v148, s93, v130
	v_add_u32_e32 v241, s26, v202
	v_add_u32_e32 v242, 0x80, v241
	s_movk_i32 s40, 0x1200
	s_cselect_b32 s40, s40, 0x2400
	s_cmp_gt_i32 s94, 15
	s_cselect_b32 s40, s40, 0
	s_lshl_b32 s40, s40, 2
	s_add_u32 s40, s68, s40
	s_addc_u32 s41, s69, 0
	s_add_i32 s43, s95, 3
	v_add_u32_e32 v131, s0, v130
	s_cmp_lt_u32 s43, 5
	v_cndmask_b32_e64 v130, v131, v148, s[36:37]
	s_cselect_b64 vcc, -1, 0
	v_add_u32_e32 v132, s26, v130
	v_cndmask_b32_e32 v130, v241, v132, vcc
	v_ashrrev_i32_e32 v131, 31, v130
	v_lshl_add_u64 v[130:131], v[130:131], 2, s[40:41]
	global_load_dwordx4 v[142:145], v[130:131], off
	v_add_u32_e32 v130, 32, v132
	v_or_b32_e32 v131, 4, v241
	v_cndmask_b32_e32 v130, v131, v130, vcc
	v_ashrrev_i32_e32 v131, 31, v130
	v_lshl_add_u64 v[130:131], v[130:131], 2, s[40:41]
	global_load_dwordx4 v[138:141], v[130:131], off
	v_add_u32_e32 v130, 0x80, v132
	v_cndmask_b32_e32 v130, v242, v130, vcc
	v_ashrrev_i32_e32 v131, 31, v130
	v_lshl_add_u64 v[130:131], v[130:131], 2, s[40:41]
	global_load_dwordx4 v[134:137], v[130:131], off
	v_add_u32_e32 v130, 0xa0, v132
	v_add_u32_e32 v131, 0x84, v241
	v_cndmask_b32_e32 v130, v131, v130, vcc
	v_ashrrev_i32_e32 v131, 31, v130
	v_lshl_add_u64 v[130:131], v[130:131], 2, s[40:41]
	global_load_dwordx4 v[130:133], v[130:131], off
	s_mov_b64 s[40:41], -1
	s_cmp_gt_i32 s95, -4
	s_cbranch_scc1 .LBB0_440
	s_andn2_b64 vcc, exec, s[40:41]
	s_cbranch_vccz .LBB0_461
